# E44: grid barrier - L1 acquire invalidate issued at arrival (workgroup is parked, polls bypass L1) instead of after the release flag; plus E42/E43 single-hop release
# speedup vs baseline: 1.0249x; 1.0131x over previous
; DI unsigned xb_ld(unsigned* p)              { return __hip_atomic_load(p, __ATOMIC_RELAXED, __HIP_MEMORY_SCOPE_AGENT); }
; DI unsigned xb_add(unsigned* p, unsigned v) { return __hip_atomic_fetch_add(p, v, __ATOMIC_RELAXED, __HIP_MEMORY_SCOPE_AGENT); }
; #define XB_SPIN(cond, bar) do { unsigned _sp = 0; while (cond) { __builtin_amdgcn_s_sleep(1); \
;     if ((++_sp & 255u) == 0u) { if (xb_ld(&(bar)[XB_TMO])) break; if (_sp > XB_SPIN_CAP) { atomicAdd(&(bar)[XB_TMO], 1u); break; } } } } while (0)
; DI void xcd_barrier(const XcdBarrier& b) {
;     ...
;         const unsigned old = xb_add(&bar[XB_XSUB(b.x)], 1u);
;         const unsigned gen = old / nloc;
;         if (old + 1u == (gen + 1u) * nloc) {
;             __builtin_amdgcn_fence(__ATOMIC_RELEASE, "agent");
;             asm volatile("s_waitcnt vmcnt(0)" ::: "memory");
;             const unsigned og = xb_add(&bar[XB_TOP], 1u);
;             const unsigned tg = og / nx;
;             if (og + 1u == (tg + 1u) * nx) xb_add(&bar[XB_TOPGEN], 1u);
;             else XB_SPIN(xb_ld(&bar[XB_TOPGEN]) == tg, bar);
;             __builtin_amdgcn_fence(__ATOMIC_ACQUIRE, "agent");
;             xb_add(&bar[XB_XGEN(b.x)], 1u);
;             asm volatile("s_waitcnt vmcnt(0)" ::: "memory");
;         } else {
;             XB_SPIN(xb_ld(&bar[XB_XGEN(b.x)]) == gen, bar);
;             __builtin_amdgcn_fence(__ATOMIC_ACQUIRE, "agent");
.LBB0_58:
	s_lshl_b32 s8, s3, 8
	s_add_u32 s8, s40, s8
	s_addc_u32 s9, s41, 0
	v_mov_b32_e32 v1, 0x1000
	v_mov_b32_e32 v3, 1
	global_atomic_add v3, v1, v3, s[8:9] offset:1024 sc0
	v_cvt_f32_u32_e32 v1, v2
	v_sub_u32_e32 v4, 0, v2
	s_add_u32 s8, s8, 0x2400
	s_addc_u32 s9, s9, 0
	v_rcp_iflag_f32_e32 v1, v1
	s_nop 0
	v_mul_f32_e32 v1, 0x4f7ffffe, v1
	v_cvt_u32_f32_e32 v1, v1
	v_mul_lo_u32 v4, v4, v1
	v_mul_hi_u32 v4, v1, v4
	v_add_u32_e32 v1, v1, v4
	s_waitcnt vmcnt(0)
	v_mul_hi_u32 v1, v3, v1
	v_mul_lo_u32 v4, v1, v2
	v_sub_u32_e32 v4, v3, v4
	v_add_u32_e32 v5, 1, v1
	v_cmp_ge_u32_e32 vcc, v4, v2
	v_add_u32_e32 v3, 1, v3
	s_nop 0
	v_cndmask_b32_e32 v1, v1, v5, vcc
	v_sub_u32_e32 v5, v4, v2
	v_cndmask_b32_e32 v4, v4, v5, vcc
	v_add_u32_e32 v5, 1, v1
	v_cmp_ge_u32_e32 vcc, v4, v2
	s_nop 1
	v_cndmask_b32_e32 v1, v1, v5, vcc
	v_mul_lo_u32 v4, v2, v1
	v_add_u32_e32 v2, v4, v2
	v_cmp_ne_u32_e32 vcc, v3, v2
	s_and_saveexec_b64 s[10:11], vcc
	s_xor_b64 s[10:11], exec, s[10:11]
	s_cbranch_execz .LBB0_72
	s_add_u32 s8, s6, 0x3300
	s_addc_u32 s9, s7, 0
	buffer_inv sc1
	s_waitcnt lgkmcnt(0)
	v_mov_b32_e32 v0, 0
	global_load_dword v2, v0, s[8:9] sc1
	s_waitcnt vmcnt(0)
	v_cmp_eq_u32_e32 vcc, v2, v1
	s_and_saveexec_b64 s[12:13], vcc
	s_cbranch_execz .LBB0_71
	s_mov_b32 s24, 1
	s_mov_b64 s[14:15], 0
	s_branch .LBB0_62

; DI unsigned xb_ld(unsigned* p)              { return __hip_atomic_load(p, __ATOMIC_RELAXED, __HIP_MEMORY_SCOPE_AGENT); }
; DI unsigned xb_add(unsigned* p, unsigned v) { return __hip_atomic_fetch_add(p, v, __ATOMIC_RELAXED, __HIP_MEMORY_SCOPE_AGENT); }
; #define XB_SPIN(cond, bar) do { unsigned _sp = 0; while (cond) { __builtin_amdgcn_s_sleep(1); \
;     if ((++_sp & 255u) == 0u) { if (xb_ld(&(bar)[XB_TMO])) break; if (_sp > XB_SPIN_CAP) { atomicAdd(&(bar)[XB_TMO], 1u); break; } } } } while (0)
; DI void xcd_barrier(const XcdBarrier& b) {
;     ...
;         if (old + 1u == (gen + 1u) * nloc) {
;             __builtin_amdgcn_fence(__ATOMIC_RELEASE, "agent");
;             asm volatile("s_waitcnt vmcnt(0)" ::: "memory");
;             const unsigned og = xb_add(&bar[XB_TOP], 1u);
;             const unsigned tg = og / nx;
;             if (og + 1u == (tg + 1u) * nx) xb_add(&bar[XB_TOPGEN], 1u);
;             else XB_SPIN(xb_ld(&bar[XB_TOPGEN]) == tg, bar);
;             __builtin_amdgcn_fence(__ATOMIC_ACQUIRE, "agent");
;             xb_add(&bar[XB_XGEN(b.x)], 1u);
;             asm volatile("s_waitcnt vmcnt(0)" ::: "memory");
;         } else {
;             XB_SPIN(xb_ld(&bar[XB_XGEN(b.x)]) == gen, bar);
;             __builtin_amdgcn_fence(__ATOMIC_ACQUIRE, "agent");
;             asm volatile("s_waitcnt vmcnt(0)" ::: "memory");
.LBB0_71:
	s_or_b64 exec, exec, s[12:13]
	s_waitcnt vmcnt(0)
	s_waitcnt vmcnt(0)
.LBB0_72:
	s_andn2_saveexec_b64 s[10:11], s[10:11]
	s_cbranch_execz .LBB0_90
	s_mov_b64 s[10:11], exec
	buffer_wbl2 sc1
	buffer_inv sc1
	s_waitcnt lgkmcnt(0)
	s_waitcnt vmcnt(0)
	v_mbcnt_lo_u32_b32 v1, s10, 0
	v_mbcnt_hi_u32_b32 v1, s11, v1
	v_cmp_eq_u32_e32 vcc, 0, v1
	s_and_saveexec_b64 s[12:13], vcc
	s_cbranch_execz .LBB0_75
	s_bcnt1_i32_b64 s10, s[10:11]
	v_mov_b32_e32 v2, 0x7000
	v_mov_b32_e32 v3, s10
	global_atomic_add v2, v2, v3, s[36:37] offset:1024 sc0

; DI unsigned xb_ld(unsigned* p)              { return __hip_atomic_load(p, __ATOMIC_RELAXED, __HIP_MEMORY_SCOPE_AGENT); }
; DI unsigned xb_add(unsigned* p, unsigned v) { return __hip_atomic_fetch_add(p, v, __ATOMIC_RELAXED, __HIP_MEMORY_SCOPE_AGENT); }
; #define XB_SPIN(cond, bar) do { unsigned _sp = 0; while (cond) { __builtin_amdgcn_s_sleep(1); \
;     if ((++_sp & 255u) == 0u) { if (xb_ld(&(bar)[XB_TMO])) break; if (_sp > XB_SPIN_CAP) { atomicAdd(&(bar)[XB_TMO], 1u); break; } } } } while (0)
; DI void xcd_barrier(const XcdBarrier& b) {
;     ...
;             else XB_SPIN(xb_ld(&bar[XB_TOPGEN]) == tg, bar);
;             __builtin_amdgcn_fence(__ATOMIC_ACQUIRE, "agent");
;             xb_add(&bar[XB_XGEN(b.x)], 1u);
;             asm volatile("s_waitcnt vmcnt(0)" ::: "memory");
.LBB0_89:
	s_or_b64 exec, exec, s[6:7]
	v_mov_b32_e32 v0, 0
	v_mov_b32_e32 v1, 1
	s_waitcnt vmcnt(0)
	s_waitcnt vmcnt(0)

; DI unsigned xb_ld(unsigned* p)              { return __hip_atomic_load(p, __ATOMIC_RELAXED, __HIP_MEMORY_SCOPE_AGENT); }
; DI unsigned xb_add(unsigned* p, unsigned v) { return __hip_atomic_fetch_add(p, v, __ATOMIC_RELAXED, __HIP_MEMORY_SCOPE_AGENT); }
; #define XB_SPIN(cond, bar) do { unsigned _sp = 0; while (cond) { __builtin_amdgcn_s_sleep(1); \
;     if ((++_sp & 255u) == 0u) { if (xb_ld(&(bar)[XB_TMO])) break; if (_sp > XB_SPIN_CAP) { atomicAdd(&(bar)[XB_TMO], 1u); break; } } } } while (0)
; DI void xcd_barrier(const XcdBarrier& b) {
;     ...
;             else XB_SPIN(xb_ld(&bar[XB_TOPGEN]) == tg, bar);
;             __builtin_amdgcn_fence(__ATOMIC_ACQUIRE, "agent");
;             xb_add(&bar[XB_XGEN(b.x)], 1u);
;             asm volatile("s_waitcnt vmcnt(0)" ::: "memory");
.LBB0_764:
	s_or_b64 exec, exec, s[4:5]
	v_readlane_b32 s4, v253, 54
	v_readlane_b32 s5, v253, 55
	s_waitcnt vmcnt(0)
	s_nop 2
	s_waitcnt vmcnt(0)

; DI unsigned xb_ld(unsigned* p)              { return __hip_atomic_load(p, __ATOMIC_RELAXED, __HIP_MEMORY_SCOPE_AGENT); }
; DI unsigned xb_add(unsigned* p, unsigned v) { return __hip_atomic_fetch_add(p, v, __ATOMIC_RELAXED, __HIP_MEMORY_SCOPE_AGENT); }
; #define XB_SPIN(cond, bar) do { unsigned _sp = 0; while (cond) { __builtin_amdgcn_s_sleep(1); \
;     if ((++_sp & 255u) == 0u) { if (xb_ld(&(bar)[XB_TMO])) break; if (_sp > XB_SPIN_CAP) { atomicAdd(&(bar)[XB_TMO], 1u); break; } } } } while (0)
; DI void xcd_barrier(const XcdBarrier& b) {
;     ...
;         const unsigned old = xb_add(&bar[XB_XSUB(b.x)], 1u);
;         const unsigned gen = old / nloc;
;         if (old + 1u == (gen + 1u) * nloc) {
;             __builtin_amdgcn_fence(__ATOMIC_RELEASE, "agent");
;             asm volatile("s_waitcnt vmcnt(0)" ::: "memory");
;             const unsigned og = xb_add(&bar[XB_TOP], 1u);
;             const unsigned tg = og / nx;
;             if (og + 1u == (tg + 1u) * nx) xb_add(&bar[XB_TOPGEN], 1u);
;             else XB_SPIN(xb_ld(&bar[XB_TOPGEN]) == tg, bar);
;             __builtin_amdgcn_fence(__ATOMIC_ACQUIRE, "agent");
;             xb_add(&bar[XB_XGEN(b.x)], 1u);
;             asm volatile("s_waitcnt vmcnt(0)" ::: "memory");
;         } else {
;             XB_SPIN(xb_ld(&bar[XB_XGEN(b.x)]) == gen, bar);
;             __builtin_amdgcn_fence(__ATOMIC_ACQUIRE, "agent");
.LBB0_1005:
	v_readlane_b32 s4, v253, 52
	v_readlane_b32 s5, v253, 53
	v_cvt_f32_u32_e32 v1, v2
	v_sub_u32_e32 v4, 0, v2
	v_rcp_iflag_f32_e32 v1, v1
	s_nop 1
	global_atomic_add v3, v173, v237, s[4:5] sc0
	v_mul_f32_e32 v1, 0x4f7ffffe, v1
	v_cvt_u32_f32_e32 v1, v1
	v_mul_lo_u32 v4, v4, v1
	v_mul_hi_u32 v4, v1, v4
	v_add_u32_e32 v1, v1, v4
	s_waitcnt vmcnt(0)
	v_mul_hi_u32 v1, v3, v1
	v_mul_lo_u32 v4, v1, v2
	v_sub_u32_e32 v4, v3, v4
	v_add_u32_e32 v5, 1, v1
	v_cmp_ge_u32_e32 vcc, v4, v2
	v_add_u32_e32 v3, 1, v3
	s_nop 0
	v_cndmask_b32_e32 v1, v1, v5, vcc
	v_sub_u32_e32 v5, v4, v2
	v_cndmask_b32_e32 v4, v4, v5, vcc
	v_add_u32_e32 v5, 1, v1
	v_cmp_ge_u32_e32 vcc, v4, v2
	s_nop 1
	v_cndmask_b32_e32 v1, v1, v5, vcc
	v_mul_lo_u32 v4, v2, v1
	v_add_u32_e32 v2, v4, v2
	v_cmp_ne_u32_e32 vcc, v3, v2
	s_and_saveexec_b64 s[4:5], vcc
	s_xor_b64 s[4:5], exec, s[4:5]
	s_cbranch_execz .LBB0_1019
	s_add_u32 s6, s62, 0x3300
	s_addc_u32 s7, s63, 0
	buffer_inv sc1
	s_waitcnt lgkmcnt(0)
	s_nop 3
	global_load_dword v0, v173, s[6:7] sc1
	s_waitcnt vmcnt(0)
	v_cmp_eq_u32_e32 vcc, v0, v1
	s_and_saveexec_b64 s[6:7], vcc
	s_cbranch_execz .LBB0_1018
	s_mov_b32 s18, 1
	s_mov_b64 s[8:9], 0
	s_branch .LBB0_1009

; DI unsigned xb_ld(unsigned* p)              { return __hip_atomic_load(p, __ATOMIC_RELAXED, __HIP_MEMORY_SCOPE_AGENT); }
; DI unsigned xb_add(unsigned* p, unsigned v) { return __hip_atomic_fetch_add(p, v, __ATOMIC_RELAXED, __HIP_MEMORY_SCOPE_AGENT); }
; #define XB_SPIN(cond, bar) do { unsigned _sp = 0; while (cond) { __builtin_amdgcn_s_sleep(1); \
;     if ((++_sp & 255u) == 0u) { if (xb_ld(&(bar)[XB_TMO])) break; if (_sp > XB_SPIN_CAP) { atomicAdd(&(bar)[XB_TMO], 1u); break; } } } } while (0)
; DI void xcd_barrier(const XcdBarrier& b) {
;     ...
;         if (old + 1u == (gen + 1u) * nloc) {
;             __builtin_amdgcn_fence(__ATOMIC_RELEASE, "agent");
;             asm volatile("s_waitcnt vmcnt(0)" ::: "memory");
;             const unsigned og = xb_add(&bar[XB_TOP], 1u);
;             const unsigned tg = og / nx;
;             if (og + 1u == (tg + 1u) * nx) xb_add(&bar[XB_TOPGEN], 1u);
;             else XB_SPIN(xb_ld(&bar[XB_TOPGEN]) == tg, bar);
;             __builtin_amdgcn_fence(__ATOMIC_ACQUIRE, "agent");
;             xb_add(&bar[XB_XGEN(b.x)], 1u);
;             asm volatile("s_waitcnt vmcnt(0)" ::: "memory");
;         } else {
;             XB_SPIN(xb_ld(&bar[XB_XGEN(b.x)]) == gen, bar);
;             __builtin_amdgcn_fence(__ATOMIC_ACQUIRE, "agent");
;             asm volatile("s_waitcnt vmcnt(0)" ::: "memory");
.LBB0_1018:
	s_or_b64 exec, exec, s[6:7]
	s_waitcnt vmcnt(0)
	s_waitcnt vmcnt(0)
.LBB0_1019:
	s_andn2_saveexec_b64 s[4:5], s[4:5]
	s_cbranch_execz .LBB0_765
	s_mov_b64 s[4:5], exec
	buffer_wbl2 sc1
	buffer_inv sc1
	s_waitcnt lgkmcnt(0)
	s_waitcnt vmcnt(0)
	v_mbcnt_lo_u32_b32 v1, s4, 0
	v_mbcnt_hi_u32_b32 v1, s5, v1
	v_cmp_eq_u32_e32 vcc, 0, v1
	s_and_saveexec_b64 s[6:7], vcc
	s_cbranch_execz .LBB0_1022
	s_bcnt1_i32_b64 s4, s[4:5]
	v_mov_b32_e32 v2, s4
	v_readlane_b32 s4, v253, 56
	v_readlane_b32 s5, v253, 57
	s_nop 4
	global_atomic_add v2, v173, v2, s[4:5] sc0
